# GEMM-1 store epilogue: staged-tile reads batched, stores via scalar-stepped row pointer
# speedup vs baseline: 1.0378x; 1.0013x over previous
; __device__ void phase_gemm1(PRef p, bf16* sA, bf16* sB) {
;     ...
;     bf16* dst;
;     int ld, c0;
;     if (ct < 14) { dst = p.ZA; ld = 1792; c0 = ct * 128; }
;     else if (ct < 18) { dst = p.ZB; ld = 512; c0 = (ct - 14) * 128; }
;     else { dst = p.ZC; ld = 768; c0 = (ct - 18) * 128; }
;     stage_tile<2>(acc, sA);
;     TILE_CHUNKS(2, sA, { *(u32x4*)(dst + (size_t)(rt * 128 + trow) * ld + c0 + tcol) = cv; })
.LBB0_304:
	v_mov_b32_e32 v0, v196
	s_load_dwordx2 s[12:13], s[20:21], 0x0
	v_cvt_pk_bf16_f32 v52, v52, v53
	v_lshrrev_b32_e32 v1, 1, v0
	v_and_b32_e32 v2, 31, v0
	v_and_or_b32 v1, v1, s75, v2
	v_and_b32_e32 v2, 64, v0
	v_lshrrev_b32_e32 v0, 2, v0
	v_and_b32_e32 v0, 8, v0
	v_lshl_or_b32 v0, v2, 1, v0
	v_mad_u64_u32 v[0:1], s[0:1], v1, s52, v[0:1]
	v_cvt_pk_bf16_f32 v53, v54, v55
	v_cvt_pk_bf16_f32 v54, v56, v57
	v_cvt_pk_bf16_f32 v55, v58, v59
	v_cvt_pk_bf16_f32 v36, v36, v37
	v_cvt_pk_bf16_f32 v37, v38, v39
	v_cvt_pk_bf16_f32 v38, v40, v41
	v_cvt_pk_bf16_f32 v39, v42, v43
	s_waitcnt lgkmcnt(0)
	s_barrier
	ds_write2_b64 v0, v[52:53], v[54:55] offset1:2
	v_cvt_pk_bf16_f32 v52, v60, v61
	v_cvt_pk_bf16_f32 v53, v62, v63
	v_cvt_pk_bf16_f32 v54, v64, v65
	v_cvt_pk_bf16_f32 v55, v66, v67
	ds_write2_b64 v0, v[36:37], v[38:39] offset0:8 offset1:10
	v_cvt_pk_bf16_f32 v36, v44, v45
	v_cvt_pk_bf16_f32 v37, v46, v47
	v_cvt_pk_bf16_f32 v38, v48, v49
	v_cvt_pk_bf16_f32 v39, v50, v51
	v_cvt_pk_bf16_f32 v20, v20, v21
	v_cvt_pk_bf16_f32 v21, v22, v23
	v_cvt_pk_bf16_f32 v22, v24, v25
	v_cvt_pk_bf16_f32 v23, v26, v27
	v_add_u32_e32 v2, 0x2000, v0
	ds_write2_b64 v0, v[52:53], v[54:55] offset0:4 offset1:6
	ds_write2_b64 v0, v[36:37], v[38:39] offset0:12 offset1:14
	ds_write2_b64 v2, v[20:21], v[22:23] offset0:64 offset1:66
	v_cvt_pk_bf16_f32 v0, v28, v29
	v_cvt_pk_bf16_f32 v1, v30, v31
	v_cvt_pk_bf16_f32 v20, v32, v33
	v_cvt_pk_bf16_f32 v21, v34, v35
	ds_write2_b64 v2, v[0:1], v[20:21] offset0:68 offset1:70
	v_cvt_pk_bf16_f32 v0, v4, v5
	v_cvt_pk_bf16_f32 v1, v6, v7
	v_cvt_pk_bf16_f32 v4, v8, v9
	v_cvt_pk_bf16_f32 v5, v10, v11
	ds_write2_b64 v2, v[0:1], v[4:5] offset0:72 offset1:74
	v_cvt_pk_bf16_f32 v0, v12, v13
	v_cvt_pk_bf16_f32 v1, v14, v15
	v_cvt_pk_bf16_f32 v4, v16, v17
	v_cvt_pk_bf16_f32 v5, v18, v19
	ds_write2_b64 v2, v[0:1], v[4:5] offset0:76 offset1:78
	v_mov_b32_e32 v2, v196
	s_waitcnt lgkmcnt(0)
	s_barrier
	s_lshl_b32 s20, s10, 7
	s_ashr_i32 s19, s18, 31
	s_lshl_b64 s[0:1], s[18:19], 1
	s_add_u32 s10, s12, s0
	s_addc_u32 s11, s13, s1
	s_mul_hi_u32 s1, s20, s14
	s_mul_i32 s0, s20, s14
	s_lshl_b64 s[0:1], s[0:1], 1
	s_add_u32 s98, s10, s0
	s_addc_u32 s99, s11, s1
	s_lshl_b32 s1, s14, 5
	v_lshrrev_b32_e32 v60, 4, v196
	v_and_b32_e32 v61, 15, v196
	v_mul_lo_u32 v62, v60, s52
	v_lshl_add_u32 v62, v61, 4, v62
	v_mul_lo_u32 v63, v60, s14
	v_lshlrev_b32_e32 v63, 1, v63
	v_lshl_add_u32 v63, v61, 4, v63
	ds_read_b128 v[20:23], v62 offset:0
	ds_read_b128 v[24:27], v62 offset:4352
	ds_read_b128 v[28:31], v62 offset:8704
	ds_read_b128 v[32:35], v62 offset:13056
	ds_read_b128 v[36:39], v62 offset:17408
	ds_read_b128 v[40:43], v62 offset:21760
	ds_read_b128 v[44:47], v62 offset:26112
	ds_read_b128 v[48:51], v62 offset:30464
	s_waitcnt lgkmcnt(7)
	global_store_dwordx4 v63, v[20:23], s[98:99]
	s_add_u32 s98, s98, s1
	s_addc_u32 s99, s99, 0
	s_waitcnt lgkmcnt(6)
	global_store_dwordx4 v63, v[24:27], s[98:99]
	s_add_u32 s98, s98, s1
	s_addc_u32 s99, s99, 0
	s_waitcnt lgkmcnt(5)
	global_store_dwordx4 v63, v[28:31], s[98:99]
	s_add_u32 s98, s98, s1
	s_addc_u32 s99, s99, 0
	s_waitcnt lgkmcnt(4)
	global_store_dwordx4 v63, v[32:35], s[98:99]
	s_add_u32 s98, s98, s1
	s_addc_u32 s99, s99, 0
	s_waitcnt lgkmcnt(3)
	global_store_dwordx4 v63, v[36:39], s[98:99]
	s_add_u32 s98, s98, s1
	s_addc_u32 s99, s99, 0
	s_waitcnt lgkmcnt(2)
	global_store_dwordx4 v63, v[40:43], s[98:99]
	s_add_u32 s98, s98, s1
	s_addc_u32 s99, s99, 0
	s_waitcnt lgkmcnt(1)
	global_store_dwordx4 v63, v[44:47], s[98:99]
	s_add_u32 s98, s98, s1
	s_addc_u32 s99, s99, 0
	s_waitcnt lgkmcnt(0)
	global_store_dwordx4 v63, v[48:51], s[98:99]
	s_add_i32 s24, s24, s81
	s_cmpk_lt_i32 s24, 0x360
	s_cbranch_scc0 .LBB0_319
